# P8 epilogue staged over the whole unit: all 64 v_exp in one run and all 64 v_rcp in one run (fewer switches between transcendental and plain VALU)
# baseline (speedup 1.0000x reference)
; #define PG8_LAS __attribute__((address_space(3)))
; __device__ __forceinline__ u32x4 pack8(f32x4 v0, f32x4 v1) { u32x4 w; w.x = cvt_pk_bf16(v0[0], v0[1]); w.y = cvt_pk_bf16(v0[2], v0[3]); w.z = cvt_pk_bf16(v1[0], v1[1]); w.w = cvt_pk_bf16(v1[2], v1[3]); return w; }
;     __device__ __forceinline__ void operator()(Acc& acc, const Unit& u, int wr, int wc, int fr, int fq, PG8_LAS unsigned char* xl) const {
;         const PG8_LAS float* S = rs_table(SS, u.r0, xl);
; #pragma unroll
;         for (int ai = 0; ai < 2; ++ai)
; #pragma unroll
;             for (int m = 0; m < 4; ++m) { const int rl = ai * HALF + wr * 64 + m * 16 + fr; const int row = u.r0 + rl; const float s = S[rl], cs = -LOG2E * s, s2 = s * s;
;                 f32x4 o[2];
; #pragma unroll
;                 for (int n = 0; n < 2; ++n) { const f32x4 g = acc[ai][0][m][n], gu = acc[ai][0][m][n] * acc[ai][1][m][n]; f32x4 r;
; #pragma unroll
;                     for (int e = 0; e < 4; ++e) r[e] = gu[e] * (s2 * __builtin_amdgcn_rcpf(1.f + __builtin_amdgcn_exp2f(cs * g[e])));
;                     o[n] = r; }
;                 *(u32x4*)(H + (size_t)row * ldc + (u.c0 >> 1) + wc * 32 + 8 * fq) = pack8(o[0], o[1]); }
.Lrs8_skip:
	ds_read_b32 v184, v148
	ds_read_b32 v186, v150
	ds_read_b32 v188, v152
	ds_read_b32 v190, v155
	ds_read_b32 v192, v157
	ds_read_b32 v194, v159
	ds_read_b32 v196, v161
	ds_read_b32 v198, v163
	s_ashr_i32 s2, s33, 1
	s_ashr_i32 s3, s2, 31
	s_lshl_b64 s[2:3], s[2:3], 1
	v_mov_b64_e32 v[170:171], s[12:13]
	v_mov_b32_e32 v180, 1.0
	v_pk_mul_f32 v[120:121], v[124:125], v[120:121]
	v_pk_mul_f32 v[122:123], v[126:127], v[122:123]
	v_pk_mul_f32 v[112:113], v[116:117], v[112:113]
	v_pk_mul_f32 v[114:115], v[118:119], v[114:115]
	v_pk_mul_f32 v[104:105], v[108:109], v[104:105]
	v_pk_mul_f32 v[106:107], v[110:111], v[106:107]
	v_pk_mul_f32 v[96:97], v[100:101], v[96:97]
	v_pk_mul_f32 v[98:99], v[102:103], v[98:99]
	v_pk_mul_f32 v[88:89], v[92:93], v[88:89]
	v_pk_mul_f32 v[90:91], v[94:95], v[90:91]
	v_pk_mul_f32 v[80:81], v[84:85], v[80:81]
	v_pk_mul_f32 v[82:83], v[86:87], v[82:83]
	v_pk_mul_f32 v[72:73], v[76:77], v[72:73]
	v_pk_mul_f32 v[74:75], v[78:79], v[74:75]
	v_pk_mul_f32 v[64:65], v[68:69], v[64:65]
	v_pk_mul_f32 v[66:67], v[70:71], v[66:67]
	v_pk_mul_f32 v[56:57], v[60:61], v[56:57]
	v_pk_mul_f32 v[58:59], v[62:63], v[58:59]
	v_pk_mul_f32 v[48:49], v[52:53], v[48:49]
	v_pk_mul_f32 v[50:51], v[54:55], v[50:51]
	v_pk_mul_f32 v[40:41], v[44:45], v[40:41]
	v_pk_mul_f32 v[42:43], v[46:47], v[42:43]
	v_pk_mul_f32 v[32:33], v[36:37], v[32:33]
	v_pk_mul_f32 v[34:35], v[38:39], v[34:35]
	v_pk_mul_f32 v[24:25], v[28:29], v[24:25]
	v_pk_mul_f32 v[26:27], v[30:31], v[26:27]
	v_pk_mul_f32 v[16:17], v[20:21], v[16:17]
	v_pk_mul_f32 v[18:19], v[22:23], v[18:19]
	v_pk_mul_f32 v[8:9], v[12:13], v[8:9]
	v_pk_mul_f32 v[10:11], v[14:15], v[10:11]
	v_pk_mul_f32 v[0:1], v[4:5], v[0:1]
	v_pk_mul_f32 v[2:3], v[6:7], v[2:3]
	s_waitcnt lgkmcnt(0)
	v_mul_f32_e32 v200, 0xbfb8aa3b, v184
	v_mul_f32_e32 v184, v184, v184
	v_mul_f32_e32 v202, 0xbfb8aa3b, v186
	v_mul_f32_e32 v186, v186, v186
	v_mul_f32_e32 v204, 0xbfb8aa3b, v188
	v_mul_f32_e32 v188, v188, v188
	v_mul_f32_e32 v206, 0xbfb8aa3b, v190
	v_mul_f32_e32 v190, v190, v190
	v_mul_f32_e32 v208, 0xbfb8aa3b, v192
	v_mul_f32_e32 v192, v192, v192
	v_mul_f32_e32 v210, 0xbfb8aa3b, v194
	v_mul_f32_e32 v194, v194, v194
	v_mul_f32_e32 v212, 0xbfb8aa3b, v196
	v_mul_f32_e32 v196, v196, v196
	v_mul_f32_e32 v214, 0xbfb8aa3b, v198
	v_mul_f32_e32 v198, v198, v198
	v_pk_mul_f32 v[124:125], v[124:125], v[200:201] op_sel_hi:[1,0]
	v_pk_mul_f32 v[126:127], v[126:127], v[200:201] op_sel_hi:[1,0]
	v_pk_mul_f32 v[116:117], v[116:117], v[200:201] op_sel_hi:[1,0]
	v_pk_mul_f32 v[118:119], v[118:119], v[200:201] op_sel_hi:[1,0]
	v_pk_mul_f32 v[108:109], v[108:109], v[202:203] op_sel_hi:[1,0]
	v_pk_mul_f32 v[110:111], v[110:111], v[202:203] op_sel_hi:[1,0]
	v_pk_mul_f32 v[100:101], v[100:101], v[202:203] op_sel_hi:[1,0]
	v_pk_mul_f32 v[102:103], v[102:103], v[202:203] op_sel_hi:[1,0]
	v_pk_mul_f32 v[92:93], v[92:93], v[204:205] op_sel_hi:[1,0]
	v_pk_mul_f32 v[94:95], v[94:95], v[204:205] op_sel_hi:[1,0]
	v_pk_mul_f32 v[84:85], v[84:85], v[204:205] op_sel_hi:[1,0]
	v_pk_mul_f32 v[86:87], v[86:87], v[204:205] op_sel_hi:[1,0]
	v_pk_mul_f32 v[76:77], v[76:77], v[206:207] op_sel_hi:[1,0]
	v_pk_mul_f32 v[78:79], v[78:79], v[206:207] op_sel_hi:[1,0]
	v_pk_mul_f32 v[68:69], v[68:69], v[206:207] op_sel_hi:[1,0]
	v_pk_mul_f32 v[70:71], v[70:71], v[206:207] op_sel_hi:[1,0]
	v_pk_mul_f32 v[60:61], v[60:61], v[208:209] op_sel_hi:[1,0]
	v_pk_mul_f32 v[62:63], v[62:63], v[208:209] op_sel_hi:[1,0]
	v_pk_mul_f32 v[52:53], v[52:53], v[208:209] op_sel_hi:[1,0]
	v_pk_mul_f32 v[54:55], v[54:55], v[208:209] op_sel_hi:[1,0]
	v_pk_mul_f32 v[44:45], v[44:45], v[210:211] op_sel_hi:[1,0]
	v_pk_mul_f32 v[46:47], v[46:47], v[210:211] op_sel_hi:[1,0]
	v_pk_mul_f32 v[36:37], v[36:37], v[210:211] op_sel_hi:[1,0]
	v_pk_mul_f32 v[38:39], v[38:39], v[210:211] op_sel_hi:[1,0]
	v_pk_mul_f32 v[28:29], v[28:29], v[212:213] op_sel_hi:[1,0]
	v_pk_mul_f32 v[30:31], v[30:31], v[212:213] op_sel_hi:[1,0]
	v_pk_mul_f32 v[20:21], v[20:21], v[212:213] op_sel_hi:[1,0]
	v_pk_mul_f32 v[22:23], v[22:23], v[212:213] op_sel_hi:[1,0]
	v_pk_mul_f32 v[12:13], v[12:13], v[214:215] op_sel_hi:[1,0]
	v_pk_mul_f32 v[14:15], v[14:15], v[214:215] op_sel_hi:[1,0]
	v_pk_mul_f32 v[4:5], v[4:5], v[214:215] op_sel_hi:[1,0]
	v_pk_mul_f32 v[6:7], v[6:7], v[214:215] op_sel_hi:[1,0]
	v_exp_f32_e32 v124, v124
	v_exp_f32_e32 v125, v125
	v_exp_f32_e32 v126, v126
	v_exp_f32_e32 v127, v127
	v_exp_f32_e32 v116, v116
	v_exp_f32_e32 v117, v117
	v_exp_f32_e32 v118, v118
	v_exp_f32_e32 v119, v119
	v_exp_f32_e32 v108, v108
	v_exp_f32_e32 v109, v109
	v_exp_f32_e32 v110, v110
	v_exp_f32_e32 v111, v111
	v_exp_f32_e32 v100, v100
	v_exp_f32_e32 v101, v101
	v_exp_f32_e32 v102, v102
	v_exp_f32_e32 v103, v103
	v_exp_f32_e32 v92, v92
	v_exp_f32_e32 v93, v93
	v_exp_f32_e32 v94, v94
	v_exp_f32_e32 v95, v95
	v_exp_f32_e32 v84, v84
	v_exp_f32_e32 v85, v85
	v_exp_f32_e32 v86, v86
	v_exp_f32_e32 v87, v87
	v_exp_f32_e32 v76, v76
	v_exp_f32_e32 v77, v77
	v_exp_f32_e32 v78, v78
	v_exp_f32_e32 v79, v79
	v_exp_f32_e32 v68, v68
	v_exp_f32_e32 v69, v69
	v_exp_f32_e32 v70, v70
	v_exp_f32_e32 v71, v71
	v_exp_f32_e32 v60, v60
	v_exp_f32_e32 v61, v61
	v_exp_f32_e32 v62, v62
	v_exp_f32_e32 v63, v63
	v_exp_f32_e32 v52, v52
	v_exp_f32_e32 v53, v53
	v_exp_f32_e32 v54, v54
	v_exp_f32_e32 v55, v55
	v_exp_f32_e32 v44, v44
	v_exp_f32_e32 v45, v45
	v_exp_f32_e32 v46, v46
	v_exp_f32_e32 v47, v47
	v_exp_f32_e32 v36, v36
	v_exp_f32_e32 v37, v37
	v_exp_f32_e32 v38, v38
	v_exp_f32_e32 v39, v39
	v_exp_f32_e32 v28, v28
	v_exp_f32_e32 v29, v29
	v_exp_f32_e32 v30, v30
	v_exp_f32_e32 v31, v31
	v_exp_f32_e32 v20, v20
	v_exp_f32_e32 v21, v21
	v_exp_f32_e32 v22, v22
; __device__ __forceinline__ u32x4 pack8(f32x4 v0, f32x4 v1) { u32x4 w; w.x = cvt_pk_bf16(v0[0], v0[1]); w.y = cvt_pk_bf16(v0[2], v0[3]); w.z = cvt_pk_bf16(v1[0], v1[1]); w.w = cvt_pk_bf16(v1[2], v1[3]); return w; }
;     __device__ __forceinline__ void operator()(Acc& acc, const Unit& u, int wr, int wc, int fr, int fq, PG8_LAS unsigned char* xl) const {
;     ...
;             for (int m = 0; m < 4; ++m) { const int rl = ai * HALF + wr * 64 + m * 16 + fr; const int row = u.r0 + rl; const float s = S[rl], cs = -LOG2E * s, s2 = s * s;
;                 f32x4 o[2];
; #pragma unroll
;                 for (int n = 0; n < 2; ++n) { const f32x4 g = acc[ai][0][m][n], gu = acc[ai][0][m][n] * acc[ai][1][m][n]; f32x4 r;
; #pragma unroll
;                     for (int e = 0; e < 4; ++e) r[e] = gu[e] * (s2 * __builtin_amdgcn_rcpf(1.f + __builtin_amdgcn_exp2f(cs * g[e])));
;                     o[n] = r; }
;                 *(u32x4*)(H + (size_t)row * ldc + (u.c0 >> 1) + wc * 32 + 8 * fq) = pack8(o[0], o[1]); }
	v_exp_f32_e32 v23, v23
	v_exp_f32_e32 v12, v12
	v_exp_f32_e32 v13, v13
	v_exp_f32_e32 v14, v14
	v_exp_f32_e32 v15, v15
	v_exp_f32_e32 v4, v4
	v_exp_f32_e32 v5, v5
	v_exp_f32_e32 v6, v6
	v_exp_f32_e32 v7, v7
	v_pk_add_f32 v[124:125], v[124:125], v[180:181] op_sel_hi:[1,0]
	v_pk_add_f32 v[126:127], v[126:127], v[180:181] op_sel_hi:[1,0]
	v_pk_add_f32 v[116:117], v[116:117], v[180:181] op_sel_hi:[1,0]
	v_pk_add_f32 v[118:119], v[118:119], v[180:181] op_sel_hi:[1,0]
	v_pk_add_f32 v[108:109], v[108:109], v[180:181] op_sel_hi:[1,0]
	v_pk_add_f32 v[110:111], v[110:111], v[180:181] op_sel_hi:[1,0]
	v_pk_add_f32 v[100:101], v[100:101], v[180:181] op_sel_hi:[1,0]
	v_pk_add_f32 v[102:103], v[102:103], v[180:181] op_sel_hi:[1,0]
	v_pk_add_f32 v[92:93], v[92:93], v[180:181] op_sel_hi:[1,0]
	v_pk_add_f32 v[94:95], v[94:95], v[180:181] op_sel_hi:[1,0]
	v_pk_add_f32 v[84:85], v[84:85], v[180:181] op_sel_hi:[1,0]
	v_pk_add_f32 v[86:87], v[86:87], v[180:181] op_sel_hi:[1,0]
	v_pk_add_f32 v[76:77], v[76:77], v[180:181] op_sel_hi:[1,0]
	v_pk_add_f32 v[78:79], v[78:79], v[180:181] op_sel_hi:[1,0]
	v_pk_add_f32 v[68:69], v[68:69], v[180:181] op_sel_hi:[1,0]
	v_pk_add_f32 v[70:71], v[70:71], v[180:181] op_sel_hi:[1,0]
	v_pk_add_f32 v[60:61], v[60:61], v[180:181] op_sel_hi:[1,0]
	v_pk_add_f32 v[62:63], v[62:63], v[180:181] op_sel_hi:[1,0]
	v_pk_add_f32 v[52:53], v[52:53], v[180:181] op_sel_hi:[1,0]
	v_pk_add_f32 v[54:55], v[54:55], v[180:181] op_sel_hi:[1,0]
	v_pk_add_f32 v[44:45], v[44:45], v[180:181] op_sel_hi:[1,0]
	v_pk_add_f32 v[46:47], v[46:47], v[180:181] op_sel_hi:[1,0]
	v_pk_add_f32 v[36:37], v[36:37], v[180:181] op_sel_hi:[1,0]
	v_pk_add_f32 v[38:39], v[38:39], v[180:181] op_sel_hi:[1,0]
	v_pk_add_f32 v[28:29], v[28:29], v[180:181] op_sel_hi:[1,0]
	v_pk_add_f32 v[30:31], v[30:31], v[180:181] op_sel_hi:[1,0]
	v_pk_add_f32 v[20:21], v[20:21], v[180:181] op_sel_hi:[1,0]
	v_pk_add_f32 v[22:23], v[22:23], v[180:181] op_sel_hi:[1,0]
	v_pk_add_f32 v[12:13], v[12:13], v[180:181] op_sel_hi:[1,0]
	v_pk_add_f32 v[14:15], v[14:15], v[180:181] op_sel_hi:[1,0]
	v_pk_add_f32 v[4:5], v[4:5], v[180:181] op_sel_hi:[1,0]
	v_pk_add_f32 v[6:7], v[6:7], v[180:181] op_sel_hi:[1,0]
	v_rcp_f32_e32 v124, v124
	v_rcp_f32_e32 v125, v125
	v_rcp_f32_e32 v126, v126
	v_rcp_f32_e32 v127, v127
	v_rcp_f32_e32 v116, v116
	v_rcp_f32_e32 v117, v117
	v_rcp_f32_e32 v118, v118
	v_rcp_f32_e32 v119, v119
	v_rcp_f32_e32 v108, v108
	v_rcp_f32_e32 v109, v109
	v_rcp_f32_e32 v110, v110
	v_rcp_f32_e32 v111, v111
	v_rcp_f32_e32 v100, v100
	v_rcp_f32_e32 v101, v101
	v_rcp_f32_e32 v102, v102
	v_rcp_f32_e32 v103, v103
	v_rcp_f32_e32 v92, v92
	v_rcp_f32_e32 v93, v93
	v_rcp_f32_e32 v94, v94
	v_rcp_f32_e32 v95, v95
	v_rcp_f32_e32 v84, v84
	v_rcp_f32_e32 v85, v85
	v_rcp_f32_e32 v86, v86
	v_rcp_f32_e32 v87, v87
	v_rcp_f32_e32 v76, v76
	v_rcp_f32_e32 v77, v77
	v_rcp_f32_e32 v78, v78
	v_rcp_f32_e32 v79, v79
	v_rcp_f32_e32 v68, v68
	v_rcp_f32_e32 v69, v69
	v_rcp_f32_e32 v70, v70
	v_rcp_f32_e32 v71, v71
	v_rcp_f32_e32 v60, v60
	v_rcp_f32_e32 v61, v61
	v_rcp_f32_e32 v62, v62
	v_rcp_f32_e32 v63, v63
	v_rcp_f32_e32 v52, v52
	v_rcp_f32_e32 v53, v53
	v_rcp_f32_e32 v54, v54
	v_rcp_f32_e32 v55, v55
	v_rcp_f32_e32 v44, v44
	v_rcp_f32_e32 v45, v45
	v_rcp_f32_e32 v46, v46
	v_rcp_f32_e32 v47, v47
	v_rcp_f32_e32 v36, v36
	v_rcp_f32_e32 v37, v37
	v_rcp_f32_e32 v38, v38
	v_rcp_f32_e32 v39, v39
	v_rcp_f32_e32 v28, v28
	v_rcp_f32_e32 v29, v29
	v_rcp_f32_e32 v30, v30
	v_rcp_f32_e32 v31, v31
	v_rcp_f32_e32 v20, v20
	v_rcp_f32_e32 v21, v21
	v_rcp_f32_e32 v22, v22
	v_rcp_f32_e32 v23, v23
	v_rcp_f32_e32 v12, v12
	v_rcp_f32_e32 v13, v13
	v_rcp_f32_e32 v14, v14
	v_rcp_f32_e32 v15, v15
	v_rcp_f32_e32 v4, v4
	v_rcp_f32_e32 v5, v5
	v_rcp_f32_e32 v6, v6
	v_rcp_f32_e32 v7, v7
	v_add_u32_e32 v172, s60, v146
	v_mad_i64_i32 v[172:173], s[30:31], v172, s64, v[170:171]
	v_lshl_add_u64 v[172:173], v[172:173], 0, s[2:3]
	v_lshl_add_u64 v[172:173], v[172:173], 0, s[8:9]
	v_lshl_add_u64 v[172:173], v[172:173], 0, v[136:137]
	v_pk_mul_f32 v[124:125], v[124:125], v[184:185] op_sel_hi:[1,0]
	v_pk_mul_f32 v[126:127], v[126:127], v[184:185] op_sel_hi:[1,0]
	v_pk_mul_f32 v[116:117], v[116:117], v[184:185] op_sel_hi:[1,0]
	v_pk_mul_f32 v[118:119], v[118:119], v[184:185] op_sel_hi:[1,0]
	v_pk_mul_f32 v[120:121], v[120:121], v[124:125]
	v_pk_mul_f32 v[122:123], v[122:123], v[126:127]
	v_pk_mul_f32 v[112:113], v[112:113], v[116:117]
	v_pk_mul_f32 v[114:115], v[114:115], v[118:119]
	v_cvt_pk_bf16_f32 v124, v120, v121
	v_cvt_pk_bf16_f32 v125, v122, v123
	v_cvt_pk_bf16_f32 v126, v112, v113
	v_cvt_pk_bf16_f32 v127, v114, v115
	flat_store_dwordx4 v[172:173], v[124:127]
	v_add_co_u32_e32 v172, vcc, 0x16000, v172
	v_pk_mul_f32 v[108:109], v[108:109], v[186:187] op_sel_hi:[1,0]
; __device__ __forceinline__ u32x4 pack8(f32x4 v0, f32x4 v1) { u32x4 w; w.x = cvt_pk_bf16(v0[0], v0[1]); w.y = cvt_pk_bf16(v0[2], v0[3]); w.z = cvt_pk_bf16(v1[0], v1[1]); w.w = cvt_pk_bf16(v1[2], v1[3]); return w; }
;     __device__ __forceinline__ void operator()(Acc& acc, const Unit& u, int wr, int wc, int fr, int fq, PG8_LAS unsigned char* xl) const {
;     ...
;             for (int m = 0; m < 4; ++m) { const int rl = ai * HALF + wr * 64 + m * 16 + fr; const int row = u.r0 + rl; const float s = S[rl], cs = -LOG2E * s, s2 = s * s;
;                 f32x4 o[2];
; #pragma unroll
;                 for (int n = 0; n < 2; ++n) { const f32x4 g = acc[ai][0][m][n], gu = acc[ai][0][m][n] * acc[ai][1][m][n]; f32x4 r;
; #pragma unroll
;                     for (int e = 0; e < 4; ++e) r[e] = gu[e] * (s2 * __builtin_amdgcn_rcpf(1.f + __builtin_amdgcn_exp2f(cs * g[e])));
;                     o[n] = r; }
;                 *(u32x4*)(H + (size_t)row * ldc + (u.c0 >> 1) + wc * 32 + 8 * fq) = pack8(o[0], o[1]); }
	v_pk_mul_f32 v[110:111], v[110:111], v[186:187] op_sel_hi:[1,0]
	v_pk_mul_f32 v[100:101], v[100:101], v[186:187] op_sel_hi:[1,0]
	v_pk_mul_f32 v[102:103], v[102:103], v[186:187] op_sel_hi:[1,0]
	v_addc_co_u32_e32 v173, vcc, 0, v173, vcc
	v_pk_mul_f32 v[104:105], v[104:105], v[108:109]
	v_pk_mul_f32 v[106:107], v[106:107], v[110:111]
	v_pk_mul_f32 v[96:97], v[96:97], v[100:101]
	v_pk_mul_f32 v[98:99], v[98:99], v[102:103]
	v_cvt_pk_bf16_f32 v108, v104, v105
	v_cvt_pk_bf16_f32 v109, v106, v107
	v_cvt_pk_bf16_f32 v110, v96, v97
	v_cvt_pk_bf16_f32 v111, v98, v99
	flat_store_dwordx4 v[172:173], v[108:111]
	v_add_co_u32_e32 v172, vcc, 0x16000, v172
	v_pk_mul_f32 v[92:93], v[92:93], v[188:189] op_sel_hi:[1,0]
	v_pk_mul_f32 v[94:95], v[94:95], v[188:189] op_sel_hi:[1,0]
	v_pk_mul_f32 v[84:85], v[84:85], v[188:189] op_sel_hi:[1,0]
	v_pk_mul_f32 v[86:87], v[86:87], v[188:189] op_sel_hi:[1,0]
	v_addc_co_u32_e32 v173, vcc, 0, v173, vcc
	v_pk_mul_f32 v[88:89], v[88:89], v[92:93]
	v_pk_mul_f32 v[90:91], v[90:91], v[94:95]
	v_pk_mul_f32 v[80:81], v[80:81], v[84:85]
	v_pk_mul_f32 v[82:83], v[82:83], v[86:87]
	v_cvt_pk_bf16_f32 v92, v88, v89
	v_cvt_pk_bf16_f32 v93, v90, v91
	v_cvt_pk_bf16_f32 v94, v80, v81
	v_cvt_pk_bf16_f32 v95, v82, v83
	flat_store_dwordx4 v[172:173], v[92:95]
	v_add_co_u32_e32 v172, vcc, 0x16000, v172
	v_pk_mul_f32 v[76:77], v[76:77], v[190:191] op_sel_hi:[1,0]
	v_pk_mul_f32 v[78:79], v[78:79], v[190:191] op_sel_hi:[1,0]
	v_pk_mul_f32 v[68:69], v[68:69], v[190:191] op_sel_hi:[1,0]
	v_pk_mul_f32 v[70:71], v[70:71], v[190:191] op_sel_hi:[1,0]
	v_addc_co_u32_e32 v173, vcc, 0, v173, vcc
	v_pk_mul_f32 v[72:73], v[72:73], v[76:77]
	v_pk_mul_f32 v[74:75], v[74:75], v[78:79]
	v_pk_mul_f32 v[64:65], v[64:65], v[68:69]
	v_pk_mul_f32 v[66:67], v[66:67], v[70:71]
	v_cvt_pk_bf16_f32 v76, v72, v73
	v_cvt_pk_bf16_f32 v77, v74, v75
	v_cvt_pk_bf16_f32 v78, v64, v65
	v_cvt_pk_bf16_f32 v79, v66, v67
	flat_store_dwordx4 v[172:173], v[76:79]
	v_add_co_u32_e32 v172, vcc, 0x6e000, v172
	v_pk_mul_f32 v[60:61], v[60:61], v[192:193] op_sel_hi:[1,0]
	v_pk_mul_f32 v[62:63], v[62:63], v[192:193] op_sel_hi:[1,0]
	v_pk_mul_f32 v[52:53], v[52:53], v[192:193] op_sel_hi:[1,0]
	v_pk_mul_f32 v[54:55], v[54:55], v[192:193] op_sel_hi:[1,0]
	v_addc_co_u32_e32 v173, vcc, 0, v173, vcc
	v_pk_mul_f32 v[56:57], v[56:57], v[60:61]
	v_pk_mul_f32 v[58:59], v[58:59], v[62:63]
	v_pk_mul_f32 v[48:49], v[48:49], v[52:53]
	v_pk_mul_f32 v[50:51], v[50:51], v[54:55]
	v_cvt_pk_bf16_f32 v60, v56, v57
	v_cvt_pk_bf16_f32 v61, v58, v59
	v_cvt_pk_bf16_f32 v62, v48, v49
	v_cvt_pk_bf16_f32 v63, v50, v51
	flat_store_dwordx4 v[172:173], v[60:63]
	v_add_co_u32_e32 v172, vcc, 0x16000, v172
	v_pk_mul_f32 v[44:45], v[44:45], v[194:195] op_sel_hi:[1,0]
	v_pk_mul_f32 v[46:47], v[46:47], v[194:195] op_sel_hi:[1,0]
	v_pk_mul_f32 v[36:37], v[36:37], v[194:195] op_sel_hi:[1,0]
	v_pk_mul_f32 v[38:39], v[38:39], v[194:195] op_sel_hi:[1,0]
	v_addc_co_u32_e32 v173, vcc, 0, v173, vcc
	v_pk_mul_f32 v[40:41], v[40:41], v[44:45]
	v_pk_mul_f32 v[42:43], v[42:43], v[46:47]
	v_pk_mul_f32 v[32:33], v[32:33], v[36:37]
	v_pk_mul_f32 v[34:35], v[34:35], v[38:39]
	v_cvt_pk_bf16_f32 v44, v40, v41
	v_cvt_pk_bf16_f32 v45, v42, v43
	v_cvt_pk_bf16_f32 v46, v32, v33
	v_cvt_pk_bf16_f32 v47, v34, v35
	flat_store_dwordx4 v[172:173], v[44:47]
	v_add_co_u32_e32 v172, vcc, 0x16000, v172
	v_pk_mul_f32 v[28:29], v[28:29], v[196:197] op_sel_hi:[1,0]
	v_pk_mul_f32 v[30:31], v[30:31], v[196:197] op_sel_hi:[1,0]
	v_pk_mul_f32 v[20:21], v[20:21], v[196:197] op_sel_hi:[1,0]
	v_pk_mul_f32 v[22:23], v[22:23], v[196:197] op_sel_hi:[1,0]
	v_addc_co_u32_e32 v173, vcc, 0, v173, vcc
	v_pk_mul_f32 v[24:25], v[24:25], v[28:29]
	v_pk_mul_f32 v[26:27], v[26:27], v[30:31]
	v_pk_mul_f32 v[16:17], v[16:17], v[20:21]
	v_pk_mul_f32 v[18:19], v[18:19], v[22:23]
	v_cvt_pk_bf16_f32 v28, v24, v25
	v_cvt_pk_bf16_f32 v29, v26, v27
	v_cvt_pk_bf16_f32 v30, v16, v17
	v_cvt_pk_bf16_f32 v31, v18, v19
	flat_store_dwordx4 v[172:173], v[28:31]
	v_add_co_u32_e32 v172, vcc, 0x16000, v172
	v_pk_mul_f32 v[12:13], v[12:13], v[198:199] op_sel_hi:[1,0]
	v_pk_mul_f32 v[14:15], v[14:15], v[198:199] op_sel_hi:[1,0]
	v_pk_mul_f32 v[4:5], v[4:5], v[198:199] op_sel_hi:[1,0]
	v_pk_mul_f32 v[6:7], v[6:7], v[198:199] op_sel_hi:[1,0]
	v_addc_co_u32_e32 v173, vcc, 0, v173, vcc
	v_pk_mul_f32 v[8:9], v[8:9], v[12:13]
	v_pk_mul_f32 v[10:11], v[10:11], v[14:15]
	v_pk_mul_f32 v[0:1], v[0:1], v[4:5]
	v_pk_mul_f32 v[2:3], v[2:3], v[6:7]
	v_cvt_pk_bf16_f32 v12, v8, v9
	v_cvt_pk_bf16_f32 v13, v10, v11
	v_cvt_pk_bf16_f32 v14, v0, v1
	v_cvt_pk_bf16_f32 v15, v2, v3
	flat_store_dwordx4 v[172:173], v[12:15]
	s_andn2_b64 vcc, exec, s[6:7]
	s_mov_b64 s[2:3], -1
	s_cbranch_vccnz .LBB0_821
	s_andn2_b64 vcc, exec, s[10:11]
	s_cbranch_vccnz .LBB0_820
	s_barrier
	s_branch .LBB0_820
